# IN GEMM K-loop: loop-end scalar updates and loop-top scalar set-up moved into the preceding phase-3 MFMA block (first ds_read issues right after the barrier)
# baseline (speedup 1.0000x reference)
.Lin_zskip:
	s_add_u32 s10, s8, 0xfff80080
	s_addc_u32 s11, s9, -1
	s_add_i32 s60, 0, 0x10000
	s_cmp_eq_u32 s59, 28
	s_cselect_b32 s15, s0, s11
	s_cselect_b32 s14, s1, s10
	v_add_u32_e32 v0, s60, v167
	s_cselect_b32 s11, s25, s58
	s_cselect_b32 s10, s27, s57
	s_add_i32 s62, 0, 0x14000
	ds_read_b128 v[130:133], v0
	ds_read_b128 v[158:161], v0 offset:1024
	ds_read_b128 v[162:165], v0 offset:2048
	ds_read_b128 v[170:173], v0 offset:3072
	v_add_u32_e32 v0, s62, v167
	ds_read_b128 v[174:177], v0
	ds_read_b128 v[178:181], v0 offset:1024
	ds_read_b128 v[182:185], v0 offset:2048
	ds_read_b128 v[186:189], v0 offset:3072
	s_mov_b32 m0, s52
	s_nop 0
	global_load_lds_dwordx4 v140, s[74:75]
	s_mov_b32 m0, s53
	s_nop 0
	global_load_lds_dwordx4 v136, s[74:75]
	s_add_i32 m0, s48, 0xc000
	ds_read_b128 v[190:193], v169
	ds_read_b128 v[194:197], v169 offset:1024
	ds_read_b128 v[198:201], v169 offset:2048
	ds_read_b128 v[216:219], v169 offset:3072
	ds_read_b128 v[220:223], v169 offset:4096
	ds_read_b128 v[224:227], v169 offset:5120
	ds_read_b128 v[228:231], v169 offset:6144
	ds_read_b128 v[232:235], v169 offset:7168
	global_load_lds_dwordx4 v156, s[8:9]
	s_add_i32 m0, s48, 0xe000
	s_nop 0
	global_load_lds_dwordx4 v146, s[8:9]
	s_waitcnt vmcnt(8)
	s_waitcnt lgkmcnt(0)
	s_barrier
	s_setprio 1
	s_waitcnt lgkmcnt(0)
	v_mfma_f32_16x16x32_bf16 v[126:129], v[130:133], v[190:193], 0
	s_add_i32 s101, s54, 1
	s_mul_i32 s76, s23, s101
	s_mul_hi_u32 s77, s22, s101
	v_mfma_f32_16x16x32_bf16 v[122:125], v[162:165], v[190:193], 0
	s_add_i32 s77, s77, s76
	s_mul_i32 s76, s22, s101
	s_add_u32 s76, s76, s2
	v_mfma_f32_16x16x32_bf16 v[110:113], v[130:133], v[198:201], 0
	s_addc_u32 s77, s77, s35
	v_cmp_lt_i64_e64 s[88:89], s[76:77], v[148:149]
	s_ashr_i32 s77, s76, 31
	v_mfma_f32_16x16x32_bf16 v[106:109], v[162:165], v[198:201], 0
	s_lshr_b32 s77, s77, 29
	s_add_i32 s77, s76, s77
	s_ashr_i32 s32, s77, 3
	v_mfma_f32_16x16x32_bf16 v[94:97], v[130:133], v[220:223], 0
	s_and_b32 s77, s77, -8
	s_sub_i32 s76, s76, s77
	s_cmp_lt_i32 s76, 0
	v_mfma_f32_16x16x32_bf16 v[90:93], v[162:165], v[220:223], 0
	s_cselect_b32 s77, s67, 0x1c0
	s_mul_i32 s76, s76, s77
	s_add_i32 s76, s76, s32
	v_mfma_f32_16x16x32_bf16 v[78:81], v[130:133], v[228:231], 0
	s_mul_hi_i32 s77, s76, 0x92492493
	s_add_i32 s77, s77, s76
	s_lshr_b32 s32, s77, 31
	v_mfma_f32_16x16x32_bf16 v[74:77], v[162:165], v[228:231], 0
	s_ashr_i32 s77, s77, 7
	s_add_i32 s77, s77, s32
	s_lshl_b32 s32, s77, 3
	v_mfma_f32_16x16x32_bf16 v[126:129], v[158:161], v[194:197], v[126:129]
	s_sub_i32 s34, 0x80, s32
	s_min_i32 s34, s34, 8
	s_abs_i32 s80, s34
	v_mfma_f32_16x16x32_bf16 v[122:125], v[170:173], v[194:197], v[122:125]
	v_cvt_f32_u32_e32 v157, s80
	s_sub_i32 s81, 0, s80
	s_mulk_i32 s77, 0xe0
	v_mfma_f32_16x16x32_bf16 v[110:113], v[158:161], v[216:219], v[110:113]
	s_sub_i32 s76, s76, s77
	v_rcp_iflag_f32_e32 v157, v157
	s_abs_i32 s77, s76
	v_mfma_f32_16x16x32_bf16 v[106:109], v[170:173], v[216:219], v[106:109]
	s_xor_b32 s100, s76, s34
	s_ashr_i32 s100, s100, 31
	v_mul_f32_e32 v157, 0x4f7ffffe, v157
	v_mfma_f32_16x16x32_bf16 v[94:97], v[158:161], v[224:227], v[94:97]
	v_cvt_u32_f32_e32 v157, v157
	s_nop 0
	v_readfirstlane_b32 s101, v157
	v_mfma_f32_16x16x32_bf16 v[90:93], v[170:173], v[224:227], v[90:93]
	s_mul_i32 s81, s81, s101
	s_mul_hi_u32 s81, s101, s81
	s_add_i32 s101, s101, s81
	v_mfma_f32_16x16x32_bf16 v[78:81], v[158:161], v[232:235], v[78:81]
	s_mul_hi_u32 s81, s77, s101
	s_mul_i32 s101, s81, s80
	s_sub_i32 s77, s77, s101
	v_mfma_f32_16x16x32_bf16 v[74:77], v[170:173], v[232:235], v[74:77]
	s_add_i32 vcc_lo, s81, 1
	s_sub_i32 s101, s77, s80
	s_cmp_ge_u32 s77, s80
	s_setprio 0
	s_setprio 1
	v_mfma_f32_16x16x32_bf16 v[118:121], v[174:177], v[190:193], 0
	s_cselect_b32 s81, vcc_lo, s81
	s_cselect_b32 s77, s101, s77
	s_add_i32 s101, s81, 1
	v_mfma_f32_16x16x32_bf16 v[114:117], v[182:185], v[190:193], 0
	s_cmp_ge_u32 s77, s80
	s_cselect_b32 s77, s101, s81
	s_xor_b32 s77, s77, s100
	v_mfma_f32_16x16x32_bf16 v[102:105], v[174:177], v[198:201], 0
	s_sub_i32 s80, s77, s100
	s_mul_i32 s77, s80, s34
	s_sub_i32 s76, s76, s77
	v_mfma_f32_16x16x32_bf16 v[98:101], v[182:185], v[198:201], 0
	s_add_i32 s81, s32, s76
	v_mfma_f32_16x16x32_bf16 v[86:89], v[174:177], v[220:223], 0
	v_mfma_f32_16x16x32_bf16 v[82:85], v[182:185], v[220:223], 0
	v_mfma_f32_16x16x32_bf16 v[70:73], v[174:177], v[228:231], 0
	v_mfma_f32_16x16x32_bf16 v[66:69], v[182:185], v[228:231], 0
	v_mfma_f32_16x16x32_bf16 v[118:121], v[178:181], v[194:197], v[118:121]
	v_mfma_f32_16x16x32_bf16 v[114:117], v[186:189], v[194:197], v[114:117]
	v_mfma_f32_16x16x32_bf16 v[102:105], v[178:181], v[216:219], v[102:105]
	v_mfma_f32_16x16x32_bf16 v[98:101], v[186:189], v[216:219], v[98:101]
	v_mfma_f32_16x16x32_bf16 v[86:89], v[178:181], v[224:227], v[86:89]
	v_mfma_f32_16x16x32_bf16 v[82:85], v[186:189], v[224:227], v[82:85]
	v_mfma_f32_16x16x32_bf16 v[70:73], v[178:181], v[232:235], v[70:73]
	v_mfma_f32_16x16x32_bf16 v[66:69], v[186:189], v[232:235], v[66:69]
	s_setprio 0
	s_barrier
	s_add_i32 s60, s60, s29
	s_add_u32 s72, s10, s44
	s_addc_u32 s73, s11, s45
	s_mov_b32 m0, s60
	ds_read_b128 v[190:193], v169 offset:16384
	ds_read_b128 v[194:197], v169 offset:17408
	ds_read_b128 v[198:201], v169 offset:18432
	ds_read_b128 v[216:219], v169 offset:19456
	ds_read_b128 v[220:223], v169 offset:20480
	ds_read_b128 v[224:227], v169 offset:21504
	ds_read_b128 v[228:231], v169 offset:22528
	ds_read_b128 v[232:235], v169 offset:23552
	global_load_lds_dwordx4 v138, s[10:11]
	s_add_i32 m0, s60, 0x2000
	s_add_u32 s60, s10, 0x80000
	s_addc_u32 s61, s11, 0
	s_add_i32 s62, s62, s29
	global_load_lds_dwordx4 v134, s[10:11]
	s_mov_b32 m0, s62
	s_add_u32 s74, s14, s44
	s_addc_u32 s75, s15, s45
	global_load_lds_dwordx4 v138, s[60:61]
	s_add_i32 m0, s62, 0x2000
	s_nop 0
	global_load_lds_dwordx4 v134, s[60:61]
	s_waitcnt vmcnt(6)
	s_waitcnt lgkmcnt(0)
	s_barrier
	s_setprio 1
	s_waitcnt lgkmcnt(0)
	v_mfma_f32_16x16x32_bf16 v[62:65], v[130:133], v[190:193], 0
	v_mfma_f32_16x16x32_bf16 v[58:61], v[162:165], v[190:193], 0
	v_mfma_f32_16x16x32_bf16 v[46:49], v[130:133], v[198:201], 0
	v_mfma_f32_16x16x32_bf16 v[42:45], v[162:165], v[198:201], 0
	v_mfma_f32_16x16x32_bf16 v[30:33], v[130:133], v[220:223], 0
	v_mfma_f32_16x16x32_bf16 v[26:29], v[162:165], v[220:223], 0
	v_mfma_f32_16x16x32_bf16 v[14:17], v[130:133], v[228:231], 0
	v_mfma_f32_16x16x32_bf16 v[10:13], v[162:165], v[228:231], 0
	v_mfma_f32_16x16x32_bf16 v[62:65], v[158:161], v[194:197], v[62:65]
	v_mfma_f32_16x16x32_bf16 v[58:61], v[170:173], v[194:197], v[58:61]
	v_mfma_f32_16x16x32_bf16 v[46:49], v[158:161], v[216:219], v[46:49]
	v_mfma_f32_16x16x32_bf16 v[42:45], v[170:173], v[216:219], v[42:45]
	v_mfma_f32_16x16x32_bf16 v[30:33], v[158:161], v[224:227], v[30:33]
	v_mfma_f32_16x16x32_bf16 v[26:29], v[170:173], v[224:227], v[26:29]
	v_mfma_f32_16x16x32_bf16 v[14:17], v[158:161], v[232:235], v[14:17]
	v_mfma_f32_16x16x32_bf16 v[10:13], v[170:173], v[232:235], v[10:13]
	s_setprio 0
	s_setprio 1
	v_mfma_f32_16x16x32_bf16 v[54:57], v[174:177], v[190:193], 0
	v_mfma_f32_16x16x32_bf16 v[50:53], v[182:185], v[190:193], 0
	v_mfma_f32_16x16x32_bf16 v[38:41], v[174:177], v[198:201], 0
	v_mfma_f32_16x16x32_bf16 v[34:37], v[182:185], v[198:201], 0
	v_mfma_f32_16x16x32_bf16 v[22:25], v[174:177], v[220:223], 0
	v_mfma_f32_16x16x32_bf16 v[18:21], v[182:185], v[220:223], 0
	v_mfma_f32_16x16x32_bf16 v[6:9], v[174:177], v[228:231], 0
	v_mfma_f32_16x16x32_bf16 v[2:5], v[182:185], v[228:231], 0
	v_mfma_f32_16x16x32_bf16 v[54:57], v[178:181], v[194:197], v[54:57]
	v_mfma_f32_16x16x32_bf16 v[50:53], v[186:189], v[194:197], v[50:53]
	v_mfma_f32_16x16x32_bf16 v[38:41], v[178:181], v[216:219], v[38:41]
	v_mfma_f32_16x16x32_bf16 v[34:37], v[186:189], v[216:219], v[34:37]
	v_mfma_f32_16x16x32_bf16 v[22:25], v[178:181], v[224:227], v[22:25]
	v_mfma_f32_16x16x32_bf16 v[18:21], v[186:189], v[224:227], v[18:21]
	v_mfma_f32_16x16x32_bf16 v[6:9], v[178:181], v[232:235], v[6:9]
	v_mfma_f32_16x16x32_bf16 v[2:5], v[186:189], v[232:235], v[2:5]
	s_setprio 0
	s_barrier
	s_add_i32 s60, 0, 0x18000
	v_add_u32_e32 v0, s60, v167
	s_add_i32 s61, 0, 0x1c000
	ds_read_b128 v[130:133], v0
	ds_read_b128 v[158:161], v0 offset:1024
	ds_read_b128 v[162:165], v0 offset:2048
	ds_read_b128 v[170:173], v0 offset:3072
	v_add_u32_e32 v0, s61, v167
	ds_read_b128 v[174:177], v0
	ds_read_b128 v[178:181], v0 offset:1024
	ds_read_b128 v[182:185], v0 offset:2048
	ds_read_b128 v[186:189], v0 offset:3072
	s_mov_b32 m0, s48
	s_nop 0
	global_load_lds_dwordx4 v140, s[14:15]
	s_mov_b32 m0, s49
	s_nop 0
	global_load_lds_dwordx4 v136, s[14:15]
	s_add_u32 s14, s14, 0x80000
	s_addc_u32 s15, s15, 0
	s_mov_b32 m0, s50
	ds_read_b128 v[190:193], v169 offset:32768
	ds_read_b128 v[194:197], v169 offset:33792
	ds_read_b128 v[198:201], v169 offset:34816
	ds_read_b128 v[216:219], v169 offset:35840
	ds_read_b128 v[220:223], v169 offset:36864
	ds_read_b128 v[224:227], v169 offset:37888
	ds_read_b128 v[228:231], v169 offset:38912
	ds_read_b128 v[232:235], v169 offset:39936
	global_load_lds_dwordx4 v140, s[14:15]
	s_mov_b32 m0, s51
	s_nop 0
	global_load_lds_dwordx4 v136, s[14:15]
	s_waitcnt vmcnt(8)
	s_waitcnt lgkmcnt(0)
	s_barrier
	s_setprio 1
	s_waitcnt lgkmcnt(0)
	v_mfma_f32_16x16x32_bf16 v[126:129], v[130:133], v[190:193], v[126:129]
	v_mfma_f32_16x16x32_bf16 v[122:125], v[162:165], v[190:193], v[122:125]
	v_mfma_f32_16x16x32_bf16 v[110:113], v[130:133], v[198:201], v[110:113]
	v_mfma_f32_16x16x32_bf16 v[106:109], v[162:165], v[198:201], v[106:109]
	v_mfma_f32_16x16x32_bf16 v[94:97], v[130:133], v[220:223], v[94:97]
	v_mfma_f32_16x16x32_bf16 v[90:93], v[162:165], v[220:223], v[90:93]
	v_mfma_f32_16x16x32_bf16 v[78:81], v[130:133], v[228:231], v[78:81]
	v_mfma_f32_16x16x32_bf16 v[74:77], v[162:165], v[228:231], v[74:77]
	v_mfma_f32_16x16x32_bf16 v[126:129], v[158:161], v[194:197], v[126:129]
	v_mfma_f32_16x16x32_bf16 v[122:125], v[170:173], v[194:197], v[122:125]
	v_mfma_f32_16x16x32_bf16 v[110:113], v[158:161], v[216:219], v[110:113]
	v_mfma_f32_16x16x32_bf16 v[106:109], v[170:173], v[216:219], v[106:109]
	v_mfma_f32_16x16x32_bf16 v[94:97], v[158:161], v[224:227], v[94:97]
	v_mfma_f32_16x16x32_bf16 v[90:93], v[170:173], v[224:227], v[90:93]
	v_mfma_f32_16x16x32_bf16 v[78:81], v[158:161], v[232:235], v[78:81]
	v_mfma_f32_16x16x32_bf16 v[74:77], v[170:173], v[232:235], v[74:77]
	s_setprio 0
	s_setprio 1
	v_mfma_f32_16x16x32_bf16 v[118:121], v[174:177], v[190:193], v[118:121]
	v_mfma_f32_16x16x32_bf16 v[114:117], v[182:185], v[190:193], v[114:117]
	v_mfma_f32_16x16x32_bf16 v[102:105], v[174:177], v[198:201], v[102:105]
	v_mfma_f32_16x16x32_bf16 v[98:101], v[182:185], v[198:201], v[98:101]
	v_mfma_f32_16x16x32_bf16 v[86:89], v[174:177], v[220:223], v[86:89]
	v_mfma_f32_16x16x32_bf16 v[82:85], v[182:185], v[220:223], v[82:85]
	v_mfma_f32_16x16x32_bf16 v[70:73], v[174:177], v[228:231], v[70:73]
	v_mfma_f32_16x16x32_bf16 v[66:69], v[182:185], v[228:231], v[66:69]
	v_mfma_f32_16x16x32_bf16 v[118:121], v[178:181], v[194:197], v[118:121]
	v_mfma_f32_16x16x32_bf16 v[114:117], v[186:189], v[194:197], v[114:117]
	v_mfma_f32_16x16x32_bf16 v[102:105], v[178:181], v[216:219], v[102:105]
	v_mfma_f32_16x16x32_bf16 v[98:101], v[186:189], v[216:219], v[98:101]
	v_mfma_f32_16x16x32_bf16 v[86:89], v[178:181], v[224:227], v[86:89]
	v_mfma_f32_16x16x32_bf16 v[82:85], v[186:189], v[224:227], v[82:85]
	v_mfma_f32_16x16x32_bf16 v[70:73], v[178:181], v[232:235], v[70:73]
	v_mfma_f32_16x16x32_bf16 v[66:69], v[186:189], v[232:235], v[66:69]
	s_setprio 0
	s_barrier
	s_add_i32 s14, s60, s29
	s_mov_b32 m0, s14
	ds_read_b128 v[190:193], v169 offset:49152
	ds_read_b128 v[194:197], v169 offset:50176
	ds_read_b128 v[198:201], v169 offset:51200
	ds_read_b128 v[216:219], v169 offset:52224
	ds_read_b128 v[220:223], v169 offset:53248
	ds_read_b128 v[224:227], v169 offset:54272
	ds_read_b128 v[228:231], v169 offset:55296
	ds_read_b128 v[232:235], v169 offset:56320
	global_load_lds_dwordx4 v138, s[72:73]
	s_add_i32 m0, s14, 0x2000
	s_add_u32 s10, s10, 0x80080
	s_addc_u32 s11, s11, 0
	s_add_i32 s14, s61, s29
	global_load_lds_dwordx4 v134, s[72:73]
	s_mov_b32 m0, s14
	s_nop 0
	global_load_lds_dwordx4 v138, s[10:11]
	s_add_i32 m0, s14, 0x2000
	s_nop 0
	global_load_lds_dwordx4 v134, s[10:11]
	s_waitcnt vmcnt(6)
	s_waitcnt lgkmcnt(0)
	s_barrier
	s_setprio 1
	s_waitcnt lgkmcnt(0)
	v_mfma_f32_16x16x32_bf16 v[62:65], v[130:133], v[190:193], v[62:65]
	s_add_i32 s59, s59, 2
	v_mfma_f32_16x16x32_bf16 v[58:61], v[162:165], v[190:193], v[58:61]
	s_add_u32 s57, s57, 0x100
	v_mfma_f32_16x16x32_bf16 v[46:49], v[130:133], v[198:201], v[46:49]
	s_addc_u32 s58, s58, 0
	v_mfma_f32_16x16x32_bf16 v[42:45], v[162:165], v[198:201], v[42:45]
	s_add_u32 s8, s8, 0x100
	v_mfma_f32_16x16x32_bf16 v[30:33], v[130:133], v[220:223], v[30:33]
	s_addc_u32 s9, s9, 0
	v_mfma_f32_16x16x32_bf16 v[26:29], v[162:165], v[220:223], v[26:29]
	s_add_u32 s10, s8, 0xfff80080
	v_mfma_f32_16x16x32_bf16 v[14:17], v[130:133], v[228:231], v[14:17]
	s_addc_u32 s11, s9, -1
	v_mfma_f32_16x16x32_bf16 v[10:13], v[162:165], v[228:231], v[10:13]
	s_add_i32 s60, 0, 0x10000
	v_mfma_f32_16x16x32_bf16 v[62:65], v[158:161], v[194:197], v[62:65]
	s_cmp_eq_u32 s59, 28
	v_mfma_f32_16x16x32_bf16 v[58:61], v[170:173], v[194:197], v[58:61]
	s_cselect_b32 s15, s0, s11
	v_mfma_f32_16x16x32_bf16 v[46:49], v[158:161], v[216:219], v[46:49]
	s_cselect_b32 s14, s1, s10
	v_mfma_f32_16x16x32_bf16 v[42:45], v[170:173], v[216:219], v[42:45]
	v_add_u32_e32 v0, s60, v167
	v_mfma_f32_16x16x32_bf16 v[30:33], v[158:161], v[224:227], v[30:33]
	s_cselect_b32 s11, s25, s58
	v_mfma_f32_16x16x32_bf16 v[26:29], v[170:173], v[224:227], v[26:29]
	s_cselect_b32 s10, s27, s57
	v_mfma_f32_16x16x32_bf16 v[14:17], v[158:161], v[232:235], v[14:17]
	s_add_i32 s62, 0, 0x14000
	v_mfma_f32_16x16x32_bf16 v[10:13], v[170:173], v[232:235], v[10:13]
	s_setprio 0
	s_setprio 1
	v_mfma_f32_16x16x32_bf16 v[54:57], v[174:177], v[190:193], v[54:57]
	v_mfma_f32_16x16x32_bf16 v[50:53], v[182:185], v[190:193], v[50:53]
	v_mfma_f32_16x16x32_bf16 v[38:41], v[174:177], v[198:201], v[38:41]
	v_mfma_f32_16x16x32_bf16 v[34:37], v[182:185], v[198:201], v[34:37]
	v_mfma_f32_16x16x32_bf16 v[22:25], v[174:177], v[220:223], v[22:25]
	v_mfma_f32_16x16x32_bf16 v[18:21], v[182:185], v[220:223], v[18:21]
	v_mfma_f32_16x16x32_bf16 v[6:9], v[174:177], v[228:231], v[6:9]
	v_mfma_f32_16x16x32_bf16 v[2:5], v[182:185], v[228:231], v[2:5]
	v_mfma_f32_16x16x32_bf16 v[54:57], v[178:181], v[194:197], v[54:57]
	v_mfma_f32_16x16x32_bf16 v[50:53], v[186:189], v[194:197], v[50:53]
	v_mfma_f32_16x16x32_bf16 v[38:41], v[178:181], v[216:219], v[38:41]
	v_mfma_f32_16x16x32_bf16 v[34:37], v[186:189], v[216:219], v[34:37]
	v_mfma_f32_16x16x32_bf16 v[22:25], v[178:181], v[224:227], v[22:25]
	v_mfma_f32_16x16x32_bf16 v[18:21], v[186:189], v[224:227], v[18:21]
	v_mfma_f32_16x16x32_bf16 v[6:9], v[178:181], v[232:235], v[6:9]
	v_mfma_f32_16x16x32_bf16 v[2:5], v[186:189], v[232:235], v[2:5]
	s_setprio 0
	s_barrier
	s_cmp_gt_u32 s59, 29
.LBB0_140:
	ds_read_b128 v[130:133], v0
	ds_read_b128 v[158:161], v0 offset:1024
	ds_read_b128 v[162:165], v0 offset:2048
	ds_read_b128 v[170:173], v0 offset:3072
	v_add_u32_e32 v0, s62, v167
	ds_read_b128 v[174:177], v0
	ds_read_b128 v[178:181], v0 offset:1024
	ds_read_b128 v[182:185], v0 offset:2048
	ds_read_b128 v[186:189], v0 offset:3072
	s_mov_b32 m0, s52
	s_nop 0
	global_load_lds_dwordx4 v140, s[74:75]
	s_mov_b32 m0, s53
	s_nop 0
	global_load_lds_dwordx4 v136, s[74:75]
	s_add_i32 m0, s48, 0xc000
	ds_read_b128 v[190:193], v169
	ds_read_b128 v[194:197], v169 offset:1024
	ds_read_b128 v[198:201], v169 offset:2048
	ds_read_b128 v[216:219], v169 offset:3072
	ds_read_b128 v[220:223], v169 offset:4096
	ds_read_b128 v[224:227], v169 offset:5120
	ds_read_b128 v[228:231], v169 offset:6144
	ds_read_b128 v[232:235], v169 offset:7168
	global_load_lds_dwordx4 v156, s[8:9]
	s_add_i32 m0, s48, 0xe000
	s_nop 0
	global_load_lds_dwordx4 v146, s[8:9]
	s_waitcnt vmcnt(8)
	s_waitcnt lgkmcnt(0)
	s_barrier
	s_setprio 1
	s_waitcnt lgkmcnt(0)
	v_mfma_f32_16x16x32_bf16 v[126:129], v[130:133], v[190:193], v[126:129]
	v_mfma_f32_16x16x32_bf16 v[122:125], v[162:165], v[190:193], v[122:125]
	v_mfma_f32_16x16x32_bf16 v[110:113], v[130:133], v[198:201], v[110:113]
	v_mfma_f32_16x16x32_bf16 v[106:109], v[162:165], v[198:201], v[106:109]
	v_mfma_f32_16x16x32_bf16 v[94:97], v[130:133], v[220:223], v[94:97]
	v_mfma_f32_16x16x32_bf16 v[90:93], v[162:165], v[220:223], v[90:93]
	v_mfma_f32_16x16x32_bf16 v[78:81], v[130:133], v[228:231], v[78:81]
	v_mfma_f32_16x16x32_bf16 v[74:77], v[162:165], v[228:231], v[74:77]
	v_mfma_f32_16x16x32_bf16 v[126:129], v[158:161], v[194:197], v[126:129]
	v_mfma_f32_16x16x32_bf16 v[122:125], v[170:173], v[194:197], v[122:125]
	v_mfma_f32_16x16x32_bf16 v[110:113], v[158:161], v[216:219], v[110:113]
	v_mfma_f32_16x16x32_bf16 v[106:109], v[170:173], v[216:219], v[106:109]
	v_mfma_f32_16x16x32_bf16 v[94:97], v[158:161], v[224:227], v[94:97]
	v_mfma_f32_16x16x32_bf16 v[90:93], v[170:173], v[224:227], v[90:93]
	v_mfma_f32_16x16x32_bf16 v[78:81], v[158:161], v[232:235], v[78:81]
	v_mfma_f32_16x16x32_bf16 v[74:77], v[170:173], v[232:235], v[74:77]
	s_setprio 0
	s_setprio 1
	v_mfma_f32_16x16x32_bf16 v[118:121], v[174:177], v[190:193], v[118:121]
	v_mfma_f32_16x16x32_bf16 v[114:117], v[182:185], v[190:193], v[114:117]
	v_mfma_f32_16x16x32_bf16 v[102:105], v[174:177], v[198:201], v[102:105]
	v_mfma_f32_16x16x32_bf16 v[98:101], v[182:185], v[198:201], v[98:101]
	v_mfma_f32_16x16x32_bf16 v[86:89], v[174:177], v[220:223], v[86:89]
	v_mfma_f32_16x16x32_bf16 v[82:85], v[182:185], v[220:223], v[82:85]
	v_mfma_f32_16x16x32_bf16 v[70:73], v[174:177], v[228:231], v[70:73]
	v_mfma_f32_16x16x32_bf16 v[66:69], v[182:185], v[228:231], v[66:69]
	v_mfma_f32_16x16x32_bf16 v[118:121], v[178:181], v[194:197], v[118:121]
	v_mfma_f32_16x16x32_bf16 v[114:117], v[186:189], v[194:197], v[114:117]
	v_mfma_f32_16x16x32_bf16 v[102:105], v[178:181], v[216:219], v[102:105]
	v_mfma_f32_16x16x32_bf16 v[98:101], v[186:189], v[216:219], v[98:101]
	v_mfma_f32_16x16x32_bf16 v[86:89], v[178:181], v[224:227], v[86:89]
	v_mfma_f32_16x16x32_bf16 v[82:85], v[186:189], v[224:227], v[82:85]
	v_mfma_f32_16x16x32_bf16 v[70:73], v[178:181], v[232:235], v[70:73]
	v_mfma_f32_16x16x32_bf16 v[66:69], v[186:189], v[232:235], v[66:69]
	s_setprio 0
	s_barrier
	s_add_i32 s60, s60, s29
	s_add_u32 s72, s10, s44
	s_addc_u32 s73, s11, s45
	s_mov_b32 m0, s60
	ds_read_b128 v[190:193], v169 offset:16384
	ds_read_b128 v[194:197], v169 offset:17408
	ds_read_b128 v[198:201], v169 offset:18432
	ds_read_b128 v[216:219], v169 offset:19456
	ds_read_b128 v[220:223], v169 offset:20480
	ds_read_b128 v[224:227], v169 offset:21504
	ds_read_b128 v[228:231], v169 offset:22528
	ds_read_b128 v[232:235], v169 offset:23552
	global_load_lds_dwordx4 v138, s[10:11]
	s_add_i32 m0, s60, 0x2000
	s_add_u32 s60, s10, 0x80000
	s_addc_u32 s61, s11, 0
	s_add_i32 s62, s62, s29
	global_load_lds_dwordx4 v134, s[10:11]
	s_mov_b32 m0, s62
	s_add_u32 s74, s14, s44
	s_addc_u32 s75, s15, s45
	global_load_lds_dwordx4 v138, s[60:61]
	s_add_i32 m0, s62, 0x2000
	s_nop 0
	global_load_lds_dwordx4 v134, s[60:61]
	s_waitcnt vmcnt(6)
	s_waitcnt lgkmcnt(0)
	s_barrier
	s_setprio 1
	s_waitcnt lgkmcnt(0)
	v_mfma_f32_16x16x32_bf16 v[62:65], v[130:133], v[190:193], v[62:65]
	v_mfma_f32_16x16x32_bf16 v[58:61], v[162:165], v[190:193], v[58:61]
	v_mfma_f32_16x16x32_bf16 v[46:49], v[130:133], v[198:201], v[46:49]
	v_mfma_f32_16x16x32_bf16 v[42:45], v[162:165], v[198:201], v[42:45]
	v_mfma_f32_16x16x32_bf16 v[30:33], v[130:133], v[220:223], v[30:33]
	v_mfma_f32_16x16x32_bf16 v[26:29], v[162:165], v[220:223], v[26:29]
	v_mfma_f32_16x16x32_bf16 v[14:17], v[130:133], v[228:231], v[14:17]
	v_mfma_f32_16x16x32_bf16 v[10:13], v[162:165], v[228:231], v[10:13]
	v_mfma_f32_16x16x32_bf16 v[62:65], v[158:161], v[194:197], v[62:65]
	v_mfma_f32_16x16x32_bf16 v[58:61], v[170:173], v[194:197], v[58:61]
	v_mfma_f32_16x16x32_bf16 v[46:49], v[158:161], v[216:219], v[46:49]
	v_mfma_f32_16x16x32_bf16 v[42:45], v[170:173], v[216:219], v[42:45]
	v_mfma_f32_16x16x32_bf16 v[30:33], v[158:161], v[224:227], v[30:33]
	v_mfma_f32_16x16x32_bf16 v[26:29], v[170:173], v[224:227], v[26:29]
	v_mfma_f32_16x16x32_bf16 v[14:17], v[158:161], v[232:235], v[14:17]
	v_mfma_f32_16x16x32_bf16 v[10:13], v[170:173], v[232:235], v[10:13]
	s_setprio 0
	s_setprio 1
	v_mfma_f32_16x16x32_bf16 v[54:57], v[174:177], v[190:193], v[54:57]
	v_mfma_f32_16x16x32_bf16 v[50:53], v[182:185], v[190:193], v[50:53]
	v_mfma_f32_16x16x32_bf16 v[38:41], v[174:177], v[198:201], v[38:41]
	v_mfma_f32_16x16x32_bf16 v[34:37], v[182:185], v[198:201], v[34:37]
	v_mfma_f32_16x16x32_bf16 v[22:25], v[174:177], v[220:223], v[22:25]
	v_mfma_f32_16x16x32_bf16 v[18:21], v[182:185], v[220:223], v[18:21]
	v_mfma_f32_16x16x32_bf16 v[6:9], v[174:177], v[228:231], v[6:9]
	v_mfma_f32_16x16x32_bf16 v[2:5], v[182:185], v[228:231], v[2:5]
	v_mfma_f32_16x16x32_bf16 v[54:57], v[178:181], v[194:197], v[54:57]
	v_mfma_f32_16x16x32_bf16 v[50:53], v[186:189], v[194:197], v[50:53]
	v_mfma_f32_16x16x32_bf16 v[38:41], v[178:181], v[216:219], v[38:41]
	v_mfma_f32_16x16x32_bf16 v[34:37], v[186:189], v[216:219], v[34:37]
	v_mfma_f32_16x16x32_bf16 v[22:25], v[178:181], v[224:227], v[22:25]
	v_mfma_f32_16x16x32_bf16 v[18:21], v[186:189], v[224:227], v[18:21]
	v_mfma_f32_16x16x32_bf16 v[6:9], v[178:181], v[232:235], v[6:9]
	v_mfma_f32_16x16x32_bf16 v[2:5], v[186:189], v[232:235], v[2:5]
	s_setprio 0
	s_barrier
	s_add_i32 s60, 0, 0x18000
	v_add_u32_e32 v0, s60, v167
	s_add_i32 s61, 0, 0x1c000
	ds_read_b128 v[130:133], v0
	ds_read_b128 v[158:161], v0 offset:1024
	ds_read_b128 v[162:165], v0 offset:2048
	ds_read_b128 v[170:173], v0 offset:3072
	v_add_u32_e32 v0, s61, v167
	ds_read_b128 v[174:177], v0
	ds_read_b128 v[178:181], v0 offset:1024
	ds_read_b128 v[182:185], v0 offset:2048
	ds_read_b128 v[186:189], v0 offset:3072
	s_mov_b32 m0, s48
	s_nop 0
	global_load_lds_dwordx4 v140, s[14:15]
	s_mov_b32 m0, s49
	s_nop 0
	global_load_lds_dwordx4 v136, s[14:15]
	s_add_u32 s14, s14, 0x80000
	s_addc_u32 s15, s15, 0
	s_mov_b32 m0, s50
	ds_read_b128 v[190:193], v169 offset:32768
	ds_read_b128 v[194:197], v169 offset:33792
	ds_read_b128 v[198:201], v169 offset:34816
	ds_read_b128 v[216:219], v169 offset:35840
	ds_read_b128 v[220:223], v169 offset:36864
	ds_read_b128 v[224:227], v169 offset:37888
	ds_read_b128 v[228:231], v169 offset:38912
	ds_read_b128 v[232:235], v169 offset:39936
	global_load_lds_dwordx4 v140, s[14:15]
	s_mov_b32 m0, s51
	s_nop 0
	global_load_lds_dwordx4 v136, s[14:15]
	s_waitcnt vmcnt(8)
	s_waitcnt lgkmcnt(0)
	s_barrier
	s_setprio 1
	s_waitcnt lgkmcnt(0)
	v_mfma_f32_16x16x32_bf16 v[126:129], v[130:133], v[190:193], v[126:129]
	v_mfma_f32_16x16x32_bf16 v[122:125], v[162:165], v[190:193], v[122:125]
	v_mfma_f32_16x16x32_bf16 v[110:113], v[130:133], v[198:201], v[110:113]
	v_mfma_f32_16x16x32_bf16 v[106:109], v[162:165], v[198:201], v[106:109]
	v_mfma_f32_16x16x32_bf16 v[94:97], v[130:133], v[220:223], v[94:97]
	v_mfma_f32_16x16x32_bf16 v[90:93], v[162:165], v[220:223], v[90:93]
	v_mfma_f32_16x16x32_bf16 v[78:81], v[130:133], v[228:231], v[78:81]
	v_mfma_f32_16x16x32_bf16 v[74:77], v[162:165], v[228:231], v[74:77]
	v_mfma_f32_16x16x32_bf16 v[126:129], v[158:161], v[194:197], v[126:129]
	v_mfma_f32_16x16x32_bf16 v[122:125], v[170:173], v[194:197], v[122:125]
	v_mfma_f32_16x16x32_bf16 v[110:113], v[158:161], v[216:219], v[110:113]
	v_mfma_f32_16x16x32_bf16 v[106:109], v[170:173], v[216:219], v[106:109]
	v_mfma_f32_16x16x32_bf16 v[94:97], v[158:161], v[224:227], v[94:97]
	v_mfma_f32_16x16x32_bf16 v[90:93], v[170:173], v[224:227], v[90:93]
	v_mfma_f32_16x16x32_bf16 v[78:81], v[158:161], v[232:235], v[78:81]
	v_mfma_f32_16x16x32_bf16 v[74:77], v[170:173], v[232:235], v[74:77]
	s_setprio 0
	s_setprio 1
	v_mfma_f32_16x16x32_bf16 v[118:121], v[174:177], v[190:193], v[118:121]
	v_mfma_f32_16x16x32_bf16 v[114:117], v[182:185], v[190:193], v[114:117]
	v_mfma_f32_16x16x32_bf16 v[102:105], v[174:177], v[198:201], v[102:105]
	v_mfma_f32_16x16x32_bf16 v[98:101], v[182:185], v[198:201], v[98:101]
	v_mfma_f32_16x16x32_bf16 v[86:89], v[174:177], v[220:223], v[86:89]
	v_mfma_f32_16x16x32_bf16 v[82:85], v[182:185], v[220:223], v[82:85]
	v_mfma_f32_16x16x32_bf16 v[70:73], v[174:177], v[228:231], v[70:73]
	v_mfma_f32_16x16x32_bf16 v[66:69], v[182:185], v[228:231], v[66:69]
	v_mfma_f32_16x16x32_bf16 v[118:121], v[178:181], v[194:197], v[118:121]
	v_mfma_f32_16x16x32_bf16 v[114:117], v[186:189], v[194:197], v[114:117]
	v_mfma_f32_16x16x32_bf16 v[102:105], v[178:181], v[216:219], v[102:105]
	v_mfma_f32_16x16x32_bf16 v[98:101], v[186:189], v[216:219], v[98:101]
	v_mfma_f32_16x16x32_bf16 v[86:89], v[178:181], v[224:227], v[86:89]
	v_mfma_f32_16x16x32_bf16 v[82:85], v[186:189], v[224:227], v[82:85]
	v_mfma_f32_16x16x32_bf16 v[70:73], v[178:181], v[232:235], v[70:73]
	v_mfma_f32_16x16x32_bf16 v[66:69], v[186:189], v[232:235], v[66:69]
	s_setprio 0
	s_barrier
	s_add_i32 s14, s60, s29
	s_mov_b32 m0, s14
	ds_read_b128 v[190:193], v169 offset:49152
	ds_read_b128 v[194:197], v169 offset:50176
	ds_read_b128 v[198:201], v169 offset:51200
	ds_read_b128 v[216:219], v169 offset:52224
	ds_read_b128 v[220:223], v169 offset:53248
	ds_read_b128 v[224:227], v169 offset:54272
	ds_read_b128 v[228:231], v169 offset:55296
	ds_read_b128 v[232:235], v169 offset:56320
	global_load_lds_dwordx4 v138, s[72:73]
	s_add_i32 m0, s14, 0x2000
	s_add_u32 s10, s10, 0x80080
	s_addc_u32 s11, s11, 0
	s_add_i32 s14, s61, s29
	global_load_lds_dwordx4 v134, s[72:73]
	s_mov_b32 m0, s14
	s_nop 0
	global_load_lds_dwordx4 v138, s[10:11]
	s_add_i32 m0, s14, 0x2000
	s_nop 0
	global_load_lds_dwordx4 v134, s[10:11]
	s_waitcnt vmcnt(6)
	s_waitcnt lgkmcnt(0)
	s_barrier
	s_setprio 1
	s_waitcnt lgkmcnt(0)
	v_mfma_f32_16x16x32_bf16 v[62:65], v[130:133], v[190:193], v[62:65]
	s_add_i32 s59, s59, 2
	v_mfma_f32_16x16x32_bf16 v[58:61], v[162:165], v[190:193], v[58:61]
	s_add_u32 s57, s57, 0x100
	v_mfma_f32_16x16x32_bf16 v[46:49], v[130:133], v[198:201], v[46:49]
	s_addc_u32 s58, s58, 0
	v_mfma_f32_16x16x32_bf16 v[42:45], v[162:165], v[198:201], v[42:45]
	s_add_u32 s8, s8, 0x100
	v_mfma_f32_16x16x32_bf16 v[30:33], v[130:133], v[220:223], v[30:33]
	s_addc_u32 s9, s9, 0
	v_mfma_f32_16x16x32_bf16 v[26:29], v[162:165], v[220:223], v[26:29]
	s_add_u32 s10, s8, 0xfff80080
	v_mfma_f32_16x16x32_bf16 v[14:17], v[130:133], v[228:231], v[14:17]
	s_addc_u32 s11, s9, -1
	v_mfma_f32_16x16x32_bf16 v[10:13], v[162:165], v[228:231], v[10:13]
	s_add_i32 s60, 0, 0x10000
	v_mfma_f32_16x16x32_bf16 v[62:65], v[158:161], v[194:197], v[62:65]
	s_cmp_eq_u32 s59, 28
	v_mfma_f32_16x16x32_bf16 v[58:61], v[170:173], v[194:197], v[58:61]
	s_cselect_b32 s15, s0, s11
	v_mfma_f32_16x16x32_bf16 v[46:49], v[158:161], v[216:219], v[46:49]
	s_cselect_b32 s14, s1, s10
	v_mfma_f32_16x16x32_bf16 v[42:45], v[170:173], v[216:219], v[42:45]
	v_add_u32_e32 v0, s60, v167
	v_mfma_f32_16x16x32_bf16 v[30:33], v[158:161], v[224:227], v[30:33]
	s_cselect_b32 s11, s25, s58
	v_mfma_f32_16x16x32_bf16 v[26:29], v[170:173], v[224:227], v[26:29]
	s_cselect_b32 s10, s27, s57
	v_mfma_f32_16x16x32_bf16 v[14:17], v[158:161], v[232:235], v[14:17]
	s_add_i32 s62, 0, 0x14000
	v_mfma_f32_16x16x32_bf16 v[10:13], v[170:173], v[232:235], v[10:13]
	s_setprio 0
	s_setprio 1
	v_mfma_f32_16x16x32_bf16 v[54:57], v[174:177], v[190:193], v[54:57]
	v_mfma_f32_16x16x32_bf16 v[50:53], v[182:185], v[190:193], v[50:53]
	v_mfma_f32_16x16x32_bf16 v[38:41], v[174:177], v[198:201], v[38:41]
	v_mfma_f32_16x16x32_bf16 v[34:37], v[182:185], v[198:201], v[34:37]
	v_mfma_f32_16x16x32_bf16 v[22:25], v[174:177], v[220:223], v[22:25]
	v_mfma_f32_16x16x32_bf16 v[18:21], v[182:185], v[220:223], v[18:21]
	v_mfma_f32_16x16x32_bf16 v[6:9], v[174:177], v[228:231], v[6:9]
	v_mfma_f32_16x16x32_bf16 v[2:5], v[182:185], v[228:231], v[2:5]
	v_mfma_f32_16x16x32_bf16 v[54:57], v[178:181], v[194:197], v[54:57]
	v_mfma_f32_16x16x32_bf16 v[50:53], v[186:189], v[194:197], v[50:53]
	v_mfma_f32_16x16x32_bf16 v[38:41], v[178:181], v[216:219], v[38:41]
	v_mfma_f32_16x16x32_bf16 v[34:37], v[186:189], v[216:219], v[34:37]
	v_mfma_f32_16x16x32_bf16 v[22:25], v[178:181], v[224:227], v[22:25]
	v_mfma_f32_16x16x32_bf16 v[18:21], v[186:189], v[224:227], v[18:21]
	v_mfma_f32_16x16x32_bf16 v[6:9], v[178:181], v[232:235], v[6:9]
	v_mfma_f32_16x16x32_bf16 v[2:5], v[186:189], v[232:235], v[2:5]
	s_setprio 0
	s_barrier
	s_cmp_gt_u32 s59, 29
	s_cbranch_scc0 .LBB0_140
	s_and_b64 vcc, exec, s[20:21]
	s_cbranch_vccz .LBB0_143
